# state pass keeps at most 48 memory operations in flight (wait before the next batch is requested); everything else as the previous best
# speedup vs baseline: 1.0082x; 1.0082x over previous
.LBB0_729:
	v_lshlrev_b32_e32 v2, 1, v8
	v_ashrrev_i32_e32 v6, 15, v8
	v_and_b32_e32 v4, 0xc000, v2
	v_and_b32_e32 v2, 0x1fff, v9
	v_lshlrev_b32_e32 v3, 2, v8
	v_ashrrev_i32_e32 v7, 31, v6
	v_lshlrev_b32_e32 v5, 1, v2
	v_and_b32_e32 v12, 0x18000, v3
	v_lshlrev_b32_e32 v13, 2, v2
	v_lshlrev_b64 v[2:3], 22, v[6:7]
	v_lshrrev_b32_e32 v10, 11, v8
	v_or3_b32 v2, v2, v4, v5
	v_lshlrev_b64 v[4:5], 10, v[6:7]
	v_lshlrev_b64 v[6:7], 23, v[6:7]
	v_and_or_b32 v4, v10, 12, v4
	v_or3_b32 v6, v6, v12, v13
	v_mov_b32_e32 v12, 0
	s_mov_b32 s2, -8
	s_waitcnt lgkmcnt(0)
	v_mov_b32_e32 v82, 0x20000
	v_mov_b32_e32 v83, 0
	v_mov_b32_e32 v84, 0x10000
	v_mov_b32_e32 v85, 0
	v_lshl_add_u64 v[74:75], s[8:9], 0, v[6:7]
	v_add_co_u32_e32 v74, vcc, 0x16100000, v74
	s_nop 1
	v_addc_co_u32_e32 v75, vcc, 0, v75, vcc
	v_lshl_add_u64 v[76:77], s[8:9], 0, v[4:5]
	v_add_co_u32_e32 v76, vcc, 0xc0000, v76
	s_nop 1
	v_addc_co_u32_e32 v77, vcc, 0, v77, vcc
	v_lshl_add_u64 v[78:79], s[8:9], 0, v[2:3]
	v_add_co_u32_e32 v78, vcc, 0x17100000, v78
	s_nop 1
	v_addc_co_u32_e32 v79, vcc, 0, v79, vcc
	global_load_dword v26, v[74:75], off
	v_lshl_add_u64 v[74:75], v[74:75], 0, v[82:83]
	global_load_dword v50, v[76:77], off
	global_load_dword v27, v[74:75], off
	v_lshl_add_u64 v[74:75], v[74:75], 0, v[82:83]
	global_load_dword v51, v[76:77], off offset:16
	global_load_dword v28, v[74:75], off
	v_lshl_add_u64 v[74:75], v[74:75], 0, v[82:83]
	global_load_dword v52, v[76:77], off offset:32
	global_load_dword v29, v[74:75], off
	v_lshl_add_u64 v[74:75], v[74:75], 0, v[82:83]
	global_load_dword v53, v[76:77], off offset:48
	global_load_dword v30, v[74:75], off
	v_lshl_add_u64 v[74:75], v[74:75], 0, v[82:83]
	global_load_dword v54, v[76:77], off offset:64
	global_load_dword v31, v[74:75], off
	v_lshl_add_u64 v[74:75], v[74:75], 0, v[82:83]
	global_load_dword v55, v[76:77], off offset:80
	global_load_dword v32, v[74:75], off
	v_lshl_add_u64 v[74:75], v[74:75], 0, v[82:83]
	global_load_dword v56, v[76:77], off offset:96
	global_load_dword v33, v[74:75], off
	v_lshl_add_u64 v[74:75], v[74:75], 0, v[82:83]
	global_load_dword v57, v[76:77], off offset:112
	global_load_dword v34, v[74:75], off
	v_lshl_add_u64 v[74:75], v[74:75], 0, v[82:83]
	global_load_dword v58, v[76:77], off offset:128
	global_load_dword v35, v[74:75], off
	v_lshl_add_u64 v[74:75], v[74:75], 0, v[82:83]
	global_load_dword v59, v[76:77], off offset:144
	global_load_dword v36, v[74:75], off
	v_lshl_add_u64 v[74:75], v[74:75], 0, v[82:83]
	global_load_dword v60, v[76:77], off offset:160
	global_load_dword v37, v[74:75], off
	v_lshl_add_u64 v[74:75], v[74:75], 0, v[82:83]
	global_load_dword v61, v[76:77], off offset:176
	global_load_dword v38, v[74:75], off
	v_lshl_add_u64 v[74:75], v[74:75], 0, v[82:83]
	global_load_dword v62, v[76:77], off offset:192
	global_load_dword v39, v[74:75], off
	v_lshl_add_u64 v[74:75], v[74:75], 0, v[82:83]
	global_load_dword v63, v[76:77], off offset:208
	global_load_dword v40, v[74:75], off
	v_lshl_add_u64 v[74:75], v[74:75], 0, v[82:83]
	global_load_dword v64, v[76:77], off offset:224
	global_load_dword v41, v[74:75], off
	v_lshl_add_u64 v[74:75], v[74:75], 0, v[82:83]
	global_load_dword v65, v[76:77], off offset:240
	s_waitcnt vmcnt(16)
	global_load_dword v42, v[74:75], off
	v_lshl_add_u64 v[74:75], v[74:75], 0, v[82:83]
	global_load_dword v66, v[76:77], off offset:256
	global_load_dword v43, v[74:75], off
	v_lshl_add_u64 v[74:75], v[74:75], 0, v[82:83]
	global_load_dword v67, v[76:77], off offset:272
	global_load_dword v44, v[74:75], off
	v_lshl_add_u64 v[74:75], v[74:75], 0, v[82:83]
	global_load_dword v68, v[76:77], off offset:288
	global_load_dword v45, v[74:75], off
	v_lshl_add_u64 v[74:75], v[74:75], 0, v[82:83]
	global_load_dword v69, v[76:77], off offset:304
	global_load_dword v46, v[74:75], off
	v_lshl_add_u64 v[74:75], v[74:75], 0, v[82:83]
	global_load_dword v70, v[76:77], off offset:320
	global_load_dword v47, v[74:75], off
	v_lshl_add_u64 v[74:75], v[74:75], 0, v[82:83]
	global_load_dword v71, v[76:77], off offset:336
	global_load_dword v48, v[74:75], off
	v_lshl_add_u64 v[74:75], v[74:75], 0, v[82:83]
	global_load_dword v72, v[76:77], off offset:352
	global_load_dword v49, v[74:75], off
	v_lshl_add_u64 v[74:75], v[74:75], 0, v[82:83]
	global_load_dword v73, v[76:77], off offset:368
	v_cvt_pk_bf16_f32 v80, v12, v11
	v_mul_f32_e32 v81, 0x3fb8aa3b, v50
	global_store_short v[78:79], v80, off
	v_exp_f32_e32 v81, v81
	v_lshl_add_u64 v[78:79], v[78:79], 0, v[84:85]
	v_fmac_f32_e32 v26, v12, v81
	v_cvt_pk_bf16_f32 v80, v26, v11
	v_mul_f32_e32 v81, 0x3fb8aa3b, v51
	global_store_short v[78:79], v80, off
	v_exp_f32_e32 v81, v81
	v_lshl_add_u64 v[78:79], v[78:79], 0, v[84:85]
	v_fmac_f32_e32 v27, v26, v81
	v_cvt_pk_bf16_f32 v80, v27, v11
	v_mul_f32_e32 v81, 0x3fb8aa3b, v52
	global_store_short v[78:79], v80, off
	v_exp_f32_e32 v81, v81
	v_lshl_add_u64 v[78:79], v[78:79], 0, v[84:85]
	v_fmac_f32_e32 v28, v27, v81
	v_cvt_pk_bf16_f32 v80, v28, v11
	v_mul_f32_e32 v81, 0x3fb8aa3b, v53
	global_store_short v[78:79], v80, off
	v_exp_f32_e32 v81, v81
	v_lshl_add_u64 v[78:79], v[78:79], 0, v[84:85]
	v_fmac_f32_e32 v29, v28, v81
	v_cvt_pk_bf16_f32 v80, v29, v11
	v_mul_f32_e32 v81, 0x3fb8aa3b, v54
	global_store_short v[78:79], v80, off
	v_exp_f32_e32 v81, v81
	v_lshl_add_u64 v[78:79], v[78:79], 0, v[84:85]
	v_fmac_f32_e32 v30, v29, v81
	v_cvt_pk_bf16_f32 v80, v30, v11
	v_mul_f32_e32 v81, 0x3fb8aa3b, v55
	global_store_short v[78:79], v80, off
	v_exp_f32_e32 v81, v81
	v_lshl_add_u64 v[78:79], v[78:79], 0, v[84:85]
	v_fmac_f32_e32 v31, v30, v81
	v_cvt_pk_bf16_f32 v80, v31, v11
	v_mul_f32_e32 v81, 0x3fb8aa3b, v56
	global_store_short v[78:79], v80, off
	v_exp_f32_e32 v81, v81
	v_lshl_add_u64 v[78:79], v[78:79], 0, v[84:85]
	v_fmac_f32_e32 v32, v31, v81
	v_cvt_pk_bf16_f32 v80, v32, v11
	v_mul_f32_e32 v81, 0x3fb8aa3b, v57
	global_store_short v[78:79], v80, off
	v_exp_f32_e32 v81, v81
	v_lshl_add_u64 v[78:79], v[78:79], 0, v[84:85]
	v_fmac_f32_e32 v33, v32, v81
	v_mov_b32_e32 v12, v33
	s_waitcnt vmcnt(24)
	global_load_dword v26, v[74:75], off
	v_lshl_add_u64 v[74:75], v[74:75], 0, v[82:83]
	global_load_dword v50, v[76:77], off offset:384
	global_load_dword v27, v[74:75], off
	v_lshl_add_u64 v[74:75], v[74:75], 0, v[82:83]
	global_load_dword v51, v[76:77], off offset:400
	global_load_dword v28, v[74:75], off
	v_lshl_add_u64 v[74:75], v[74:75], 0, v[82:83]
	global_load_dword v52, v[76:77], off offset:416
	global_load_dword v29, v[74:75], off
	v_lshl_add_u64 v[74:75], v[74:75], 0, v[82:83]
	global_load_dword v53, v[76:77], off offset:432
	global_load_dword v30, v[74:75], off
	v_lshl_add_u64 v[74:75], v[74:75], 0, v[82:83]
	global_load_dword v54, v[76:77], off offset:448
	global_load_dword v31, v[74:75], off
	v_lshl_add_u64 v[74:75], v[74:75], 0, v[82:83]
	global_load_dword v55, v[76:77], off offset:464
	global_load_dword v32, v[74:75], off
	v_lshl_add_u64 v[74:75], v[74:75], 0, v[82:83]
	global_load_dword v56, v[76:77], off offset:480
	global_load_dword v33, v[74:75], off
	v_lshl_add_u64 v[74:75], v[74:75], 0, v[82:83]
	global_load_dword v57, v[76:77], off offset:496
	v_cvt_pk_bf16_f32 v80, v12, v11
	v_mul_f32_e32 v81, 0x3fb8aa3b, v58
	global_store_short v[78:79], v80, off
	v_exp_f32_e32 v81, v81
	v_lshl_add_u64 v[78:79], v[78:79], 0, v[84:85]
	v_fmac_f32_e32 v34, v12, v81
	v_cvt_pk_bf16_f32 v80, v34, v11
	v_mul_f32_e32 v81, 0x3fb8aa3b, v59
	global_store_short v[78:79], v80, off
	v_exp_f32_e32 v81, v81
	v_lshl_add_u64 v[78:79], v[78:79], 0, v[84:85]
	v_fmac_f32_e32 v35, v34, v81
	v_cvt_pk_bf16_f32 v80, v35, v11
	v_mul_f32_e32 v81, 0x3fb8aa3b, v60
	global_store_short v[78:79], v80, off
	v_exp_f32_e32 v81, v81
	v_lshl_add_u64 v[78:79], v[78:79], 0, v[84:85]
	v_fmac_f32_e32 v36, v35, v81
	v_cvt_pk_bf16_f32 v80, v36, v11
	v_mul_f32_e32 v81, 0x3fb8aa3b, v61
	global_store_short v[78:79], v80, off
	v_exp_f32_e32 v81, v81
	v_lshl_add_u64 v[78:79], v[78:79], 0, v[84:85]
	v_fmac_f32_e32 v37, v36, v81
	v_cvt_pk_bf16_f32 v80, v37, v11
	v_mul_f32_e32 v81, 0x3fb8aa3b, v62
	global_store_short v[78:79], v80, off
	v_exp_f32_e32 v81, v81
	v_lshl_add_u64 v[78:79], v[78:79], 0, v[84:85]
	v_fmac_f32_e32 v38, v37, v81
	v_cvt_pk_bf16_f32 v80, v38, v11
	v_mul_f32_e32 v81, 0x3fb8aa3b, v63
	global_store_short v[78:79], v80, off
	v_exp_f32_e32 v81, v81
	v_lshl_add_u64 v[78:79], v[78:79], 0, v[84:85]
	v_fmac_f32_e32 v39, v38, v81
	v_cvt_pk_bf16_f32 v80, v39, v11
	v_mul_f32_e32 v81, 0x3fb8aa3b, v64
	global_store_short v[78:79], v80, off
	v_exp_f32_e32 v81, v81
	v_lshl_add_u64 v[78:79], v[78:79], 0, v[84:85]
	v_fmac_f32_e32 v40, v39, v81
	v_cvt_pk_bf16_f32 v80, v40, v11
	v_mul_f32_e32 v81, 0x3fb8aa3b, v65
	global_store_short v[78:79], v80, off
	v_exp_f32_e32 v81, v81
	v_lshl_add_u64 v[78:79], v[78:79], 0, v[84:85]
	v_fmac_f32_e32 v41, v40, v81
	v_mov_b32_e32 v12, v41
	s_waitcnt vmcnt(24)
	global_load_dword v34, v[74:75], off
	v_lshl_add_u64 v[74:75], v[74:75], 0, v[82:83]
	global_load_dword v58, v[76:77], off offset:512
	global_load_dword v35, v[74:75], off
	v_lshl_add_u64 v[74:75], v[74:75], 0, v[82:83]
	global_load_dword v59, v[76:77], off offset:528
	global_load_dword v36, v[74:75], off
	v_lshl_add_u64 v[74:75], v[74:75], 0, v[82:83]
	global_load_dword v60, v[76:77], off offset:544
	global_load_dword v37, v[74:75], off
	v_lshl_add_u64 v[74:75], v[74:75], 0, v[82:83]
	global_load_dword v61, v[76:77], off offset:560
	global_load_dword v38, v[74:75], off
	v_lshl_add_u64 v[74:75], v[74:75], 0, v[82:83]
	global_load_dword v62, v[76:77], off offset:576
	global_load_dword v39, v[74:75], off
	v_lshl_add_u64 v[74:75], v[74:75], 0, v[82:83]
	global_load_dword v63, v[76:77], off offset:592
	global_load_dword v40, v[74:75], off
	v_lshl_add_u64 v[74:75], v[74:75], 0, v[82:83]
	global_load_dword v64, v[76:77], off offset:608
	global_load_dword v41, v[74:75], off
	v_lshl_add_u64 v[74:75], v[74:75], 0, v[82:83]
	global_load_dword v65, v[76:77], off offset:624
	v_cvt_pk_bf16_f32 v80, v12, v11
	v_mul_f32_e32 v81, 0x3fb8aa3b, v66
	global_store_short v[78:79], v80, off
	v_exp_f32_e32 v81, v81
	v_lshl_add_u64 v[78:79], v[78:79], 0, v[84:85]
	v_fmac_f32_e32 v42, v12, v81
	v_cvt_pk_bf16_f32 v80, v42, v11
	v_mul_f32_e32 v81, 0x3fb8aa3b, v67
	global_store_short v[78:79], v80, off
	v_exp_f32_e32 v81, v81
	v_lshl_add_u64 v[78:79], v[78:79], 0, v[84:85]
	v_fmac_f32_e32 v43, v42, v81
	v_cvt_pk_bf16_f32 v80, v43, v11
	v_mul_f32_e32 v81, 0x3fb8aa3b, v68
	global_store_short v[78:79], v80, off
	v_exp_f32_e32 v81, v81
	v_lshl_add_u64 v[78:79], v[78:79], 0, v[84:85]
	v_fmac_f32_e32 v44, v43, v81
	v_cvt_pk_bf16_f32 v80, v44, v11
	v_mul_f32_e32 v81, 0x3fb8aa3b, v69
	global_store_short v[78:79], v80, off
	v_exp_f32_e32 v81, v81
	v_lshl_add_u64 v[78:79], v[78:79], 0, v[84:85]
	v_fmac_f32_e32 v45, v44, v81
	v_cvt_pk_bf16_f32 v80, v45, v11
	v_mul_f32_e32 v81, 0x3fb8aa3b, v70
	global_store_short v[78:79], v80, off
	v_exp_f32_e32 v81, v81
	v_lshl_add_u64 v[78:79], v[78:79], 0, v[84:85]
	v_fmac_f32_e32 v46, v45, v81
	v_cvt_pk_bf16_f32 v80, v46, v11
	v_mul_f32_e32 v81, 0x3fb8aa3b, v71
	global_store_short v[78:79], v80, off
	v_exp_f32_e32 v81, v81
	v_lshl_add_u64 v[78:79], v[78:79], 0, v[84:85]
	v_fmac_f32_e32 v47, v46, v81
	v_cvt_pk_bf16_f32 v80, v47, v11
	v_mul_f32_e32 v81, 0x3fb8aa3b, v72
	global_store_short v[78:79], v80, off
	v_exp_f32_e32 v81, v81
	v_lshl_add_u64 v[78:79], v[78:79], 0, v[84:85]
	v_fmac_f32_e32 v48, v47, v81
	v_cvt_pk_bf16_f32 v80, v48, v11
	v_mul_f32_e32 v81, 0x3fb8aa3b, v73
	global_store_short v[78:79], v80, off
	v_exp_f32_e32 v81, v81
	v_lshl_add_u64 v[78:79], v[78:79], 0, v[84:85]
	v_fmac_f32_e32 v49, v48, v81
	v_mov_b32_e32 v12, v49
	s_waitcnt vmcnt(24)
	global_load_dword v42, v[74:75], off
	v_lshl_add_u64 v[74:75], v[74:75], 0, v[82:83]
	global_load_dword v66, v[76:77], off offset:640
	global_load_dword v43, v[74:75], off
	v_lshl_add_u64 v[74:75], v[74:75], 0, v[82:83]
	global_load_dword v67, v[76:77], off offset:656
	global_load_dword v44, v[74:75], off
	v_lshl_add_u64 v[74:75], v[74:75], 0, v[82:83]
	global_load_dword v68, v[76:77], off offset:672
	global_load_dword v45, v[74:75], off
	v_lshl_add_u64 v[74:75], v[74:75], 0, v[82:83]
	global_load_dword v69, v[76:77], off offset:688
	global_load_dword v46, v[74:75], off
	v_lshl_add_u64 v[74:75], v[74:75], 0, v[82:83]
	global_load_dword v70, v[76:77], off offset:704
	global_load_dword v47, v[74:75], off
	v_lshl_add_u64 v[74:75], v[74:75], 0, v[82:83]
	global_load_dword v71, v[76:77], off offset:720
	global_load_dword v48, v[74:75], off
	v_lshl_add_u64 v[74:75], v[74:75], 0, v[82:83]
	global_load_dword v72, v[76:77], off offset:736
	global_load_dword v49, v[74:75], off
	v_lshl_add_u64 v[74:75], v[74:75], 0, v[82:83]
	global_load_dword v73, v[76:77], off offset:752
	v_cvt_pk_bf16_f32 v80, v12, v11
	v_mul_f32_e32 v81, 0x3fb8aa3b, v50
	global_store_short v[78:79], v80, off
	v_exp_f32_e32 v81, v81
	v_lshl_add_u64 v[78:79], v[78:79], 0, v[84:85]
	v_fmac_f32_e32 v26, v12, v81
	v_cvt_pk_bf16_f32 v80, v26, v11
	v_mul_f32_e32 v81, 0x3fb8aa3b, v51
	global_store_short v[78:79], v80, off
	v_exp_f32_e32 v81, v81
	v_lshl_add_u64 v[78:79], v[78:79], 0, v[84:85]
	v_fmac_f32_e32 v27, v26, v81
	v_cvt_pk_bf16_f32 v80, v27, v11
	v_mul_f32_e32 v81, 0x3fb8aa3b, v52
	global_store_short v[78:79], v80, off
	v_exp_f32_e32 v81, v81
	v_lshl_add_u64 v[78:79], v[78:79], 0, v[84:85]
	v_fmac_f32_e32 v28, v27, v81
	v_cvt_pk_bf16_f32 v80, v28, v11
	v_mul_f32_e32 v81, 0x3fb8aa3b, v53
	global_store_short v[78:79], v80, off
	v_exp_f32_e32 v81, v81
	v_lshl_add_u64 v[78:79], v[78:79], 0, v[84:85]
	v_fmac_f32_e32 v29, v28, v81
	v_cvt_pk_bf16_f32 v80, v29, v11
	v_mul_f32_e32 v81, 0x3fb8aa3b, v54
	global_store_short v[78:79], v80, off
	v_exp_f32_e32 v81, v81
	v_lshl_add_u64 v[78:79], v[78:79], 0, v[84:85]
	v_fmac_f32_e32 v30, v29, v81
	v_cvt_pk_bf16_f32 v80, v30, v11
	v_mul_f32_e32 v81, 0x3fb8aa3b, v55
	global_store_short v[78:79], v80, off
	v_exp_f32_e32 v81, v81
	v_lshl_add_u64 v[78:79], v[78:79], 0, v[84:85]
	v_fmac_f32_e32 v31, v30, v81
	v_cvt_pk_bf16_f32 v80, v31, v11
	v_mul_f32_e32 v81, 0x3fb8aa3b, v56
	global_store_short v[78:79], v80, off
	v_exp_f32_e32 v81, v81
	v_lshl_add_u64 v[78:79], v[78:79], 0, v[84:85]
	v_fmac_f32_e32 v32, v31, v81
	v_cvt_pk_bf16_f32 v80, v32, v11
	v_mul_f32_e32 v81, 0x3fb8aa3b, v57
	global_store_short v[78:79], v80, off
	v_exp_f32_e32 v81, v81
	v_lshl_add_u64 v[78:79], v[78:79], 0, v[84:85]
	v_fmac_f32_e32 v33, v32, v81
	v_mov_b32_e32 v12, v33
	s_waitcnt vmcnt(24)
	global_load_dword v26, v[74:75], off
	v_lshl_add_u64 v[74:75], v[74:75], 0, v[82:83]
	global_load_dword v50, v[76:77], off offset:768
	global_load_dword v27, v[74:75], off
	v_lshl_add_u64 v[74:75], v[74:75], 0, v[82:83]
	global_load_dword v51, v[76:77], off offset:784
	global_load_dword v28, v[74:75], off
	v_lshl_add_u64 v[74:75], v[74:75], 0, v[82:83]
	global_load_dword v52, v[76:77], off offset:800
	global_load_dword v29, v[74:75], off
	v_lshl_add_u64 v[74:75], v[74:75], 0, v[82:83]
	global_load_dword v53, v[76:77], off offset:816
	global_load_dword v30, v[74:75], off
	v_lshl_add_u64 v[74:75], v[74:75], 0, v[82:83]
	global_load_dword v54, v[76:77], off offset:832
	global_load_dword v31, v[74:75], off
	v_lshl_add_u64 v[74:75], v[74:75], 0, v[82:83]
	global_load_dword v55, v[76:77], off offset:848
	global_load_dword v32, v[74:75], off
	v_lshl_add_u64 v[74:75], v[74:75], 0, v[82:83]
	global_load_dword v56, v[76:77], off offset:864
	global_load_dword v33, v[74:75], off
	v_lshl_add_u64 v[74:75], v[74:75], 0, v[82:83]
	global_load_dword v57, v[76:77], off offset:880
	v_cvt_pk_bf16_f32 v80, v12, v11
	v_mul_f32_e32 v81, 0x3fb8aa3b, v58
	global_store_short v[78:79], v80, off
	v_exp_f32_e32 v81, v81
	v_lshl_add_u64 v[78:79], v[78:79], 0, v[84:85]
	v_fmac_f32_e32 v34, v12, v81
	v_cvt_pk_bf16_f32 v80, v34, v11
	v_mul_f32_e32 v81, 0x3fb8aa3b, v59
	global_store_short v[78:79], v80, off
	v_exp_f32_e32 v81, v81
	v_lshl_add_u64 v[78:79], v[78:79], 0, v[84:85]
	v_fmac_f32_e32 v35, v34, v81
	v_cvt_pk_bf16_f32 v80, v35, v11
	v_mul_f32_e32 v81, 0x3fb8aa3b, v60
	global_store_short v[78:79], v80, off
	v_exp_f32_e32 v81, v81
	v_lshl_add_u64 v[78:79], v[78:79], 0, v[84:85]
	v_fmac_f32_e32 v36, v35, v81
	v_cvt_pk_bf16_f32 v80, v36, v11
	v_mul_f32_e32 v81, 0x3fb8aa3b, v61
	global_store_short v[78:79], v80, off
	v_exp_f32_e32 v81, v81
	v_lshl_add_u64 v[78:79], v[78:79], 0, v[84:85]
	v_fmac_f32_e32 v37, v36, v81
	v_cvt_pk_bf16_f32 v80, v37, v11
	v_mul_f32_e32 v81, 0x3fb8aa3b, v62
	global_store_short v[78:79], v80, off
	v_exp_f32_e32 v81, v81
	v_lshl_add_u64 v[78:79], v[78:79], 0, v[84:85]
	v_fmac_f32_e32 v38, v37, v81
	v_cvt_pk_bf16_f32 v80, v38, v11
	v_mul_f32_e32 v81, 0x3fb8aa3b, v63
	global_store_short v[78:79], v80, off
	v_exp_f32_e32 v81, v81
	v_lshl_add_u64 v[78:79], v[78:79], 0, v[84:85]
	v_fmac_f32_e32 v39, v38, v81
	v_cvt_pk_bf16_f32 v80, v39, v11
	v_mul_f32_e32 v81, 0x3fb8aa3b, v64
	global_store_short v[78:79], v80, off
	v_exp_f32_e32 v81, v81
	v_lshl_add_u64 v[78:79], v[78:79], 0, v[84:85]
	v_fmac_f32_e32 v40, v39, v81
	v_cvt_pk_bf16_f32 v80, v40, v11
	v_mul_f32_e32 v81, 0x3fb8aa3b, v65
	global_store_short v[78:79], v80, off
	v_exp_f32_e32 v81, v81
	v_lshl_add_u64 v[78:79], v[78:79], 0, v[84:85]
	v_fmac_f32_e32 v41, v40, v81
	v_mov_b32_e32 v12, v41
	s_waitcnt vmcnt(24)
	global_load_dword v34, v[74:75], off
	v_lshl_add_u64 v[74:75], v[74:75], 0, v[82:83]
	global_load_dword v58, v[76:77], off offset:896
	global_load_dword v35, v[74:75], off
	v_lshl_add_u64 v[74:75], v[74:75], 0, v[82:83]
	global_load_dword v59, v[76:77], off offset:912
	global_load_dword v36, v[74:75], off
	v_lshl_add_u64 v[74:75], v[74:75], 0, v[82:83]
	global_load_dword v60, v[76:77], off offset:928
	global_load_dword v37, v[74:75], off
	v_lshl_add_u64 v[74:75], v[74:75], 0, v[82:83]
	global_load_dword v61, v[76:77], off offset:944
	global_load_dword v38, v[74:75], off
	v_lshl_add_u64 v[74:75], v[74:75], 0, v[82:83]
	global_load_dword v62, v[76:77], off offset:960
	global_load_dword v39, v[74:75], off
	v_lshl_add_u64 v[74:75], v[74:75], 0, v[82:83]
	global_load_dword v63, v[76:77], off offset:976
	global_load_dword v40, v[74:75], off
	v_lshl_add_u64 v[74:75], v[74:75], 0, v[82:83]
	global_load_dword v64, v[76:77], off offset:992
	global_load_dword v41, v[74:75], off
	v_lshl_add_u64 v[74:75], v[74:75], 0, v[82:83]
	global_load_dword v65, v[76:77], off offset:1008
	v_cvt_pk_bf16_f32 v80, v12, v11
	v_mul_f32_e32 v81, 0x3fb8aa3b, v66
	global_store_short v[78:79], v80, off
	v_exp_f32_e32 v81, v81
	v_lshl_add_u64 v[78:79], v[78:79], 0, v[84:85]
	v_fmac_f32_e32 v42, v12, v81
	v_cvt_pk_bf16_f32 v80, v42, v11
	v_mul_f32_e32 v81, 0x3fb8aa3b, v67
	global_store_short v[78:79], v80, off
	v_exp_f32_e32 v81, v81
	v_lshl_add_u64 v[78:79], v[78:79], 0, v[84:85]
	v_fmac_f32_e32 v43, v42, v81
	v_cvt_pk_bf16_f32 v80, v43, v11
	v_mul_f32_e32 v81, 0x3fb8aa3b, v68
	global_store_short v[78:79], v80, off
	v_exp_f32_e32 v81, v81
	v_lshl_add_u64 v[78:79], v[78:79], 0, v[84:85]
	v_fmac_f32_e32 v44, v43, v81
	v_cvt_pk_bf16_f32 v80, v44, v11
	v_mul_f32_e32 v81, 0x3fb8aa3b, v69
	global_store_short v[78:79], v80, off
	v_exp_f32_e32 v81, v81
	v_lshl_add_u64 v[78:79], v[78:79], 0, v[84:85]
	v_fmac_f32_e32 v45, v44, v81
	v_cvt_pk_bf16_f32 v80, v45, v11
	v_mul_f32_e32 v81, 0x3fb8aa3b, v70
	global_store_short v[78:79], v80, off
	v_exp_f32_e32 v81, v81
	v_lshl_add_u64 v[78:79], v[78:79], 0, v[84:85]
	v_fmac_f32_e32 v46, v45, v81
	v_cvt_pk_bf16_f32 v80, v46, v11
	v_mul_f32_e32 v81, 0x3fb8aa3b, v71
	global_store_short v[78:79], v80, off
	v_exp_f32_e32 v81, v81
	v_lshl_add_u64 v[78:79], v[78:79], 0, v[84:85]
	v_fmac_f32_e32 v47, v46, v81
	v_cvt_pk_bf16_f32 v80, v47, v11
	v_mul_f32_e32 v81, 0x3fb8aa3b, v72
	global_store_short v[78:79], v80, off
	v_exp_f32_e32 v81, v81
	v_lshl_add_u64 v[78:79], v[78:79], 0, v[84:85]
	v_fmac_f32_e32 v48, v47, v81
	v_cvt_pk_bf16_f32 v80, v48, v11
	v_mul_f32_e32 v81, 0x3fb8aa3b, v73
	global_store_short v[78:79], v80, off
	v_exp_f32_e32 v81, v81
	v_lshl_add_u64 v[78:79], v[78:79], 0, v[84:85]
	v_fmac_f32_e32 v49, v48, v81
	v_mov_b32_e32 v12, v49
	s_waitcnt vmcnt(24)
	v_cvt_pk_bf16_f32 v80, v12, v11
	v_mul_f32_e32 v81, 0x3fb8aa3b, v50
	global_store_short v[78:79], v80, off
	v_exp_f32_e32 v81, v81
	v_lshl_add_u64 v[78:79], v[78:79], 0, v[84:85]
	v_fmac_f32_e32 v26, v12, v81
	v_cvt_pk_bf16_f32 v80, v26, v11
	v_mul_f32_e32 v81, 0x3fb8aa3b, v51
	global_store_short v[78:79], v80, off
	v_exp_f32_e32 v81, v81
	v_lshl_add_u64 v[78:79], v[78:79], 0, v[84:85]
	v_fmac_f32_e32 v27, v26, v81
	v_cvt_pk_bf16_f32 v80, v27, v11
	v_mul_f32_e32 v81, 0x3fb8aa3b, v52
	global_store_short v[78:79], v80, off
	v_exp_f32_e32 v81, v81
	v_lshl_add_u64 v[78:79], v[78:79], 0, v[84:85]
	v_fmac_f32_e32 v28, v27, v81
	v_cvt_pk_bf16_f32 v80, v28, v11
	v_mul_f32_e32 v81, 0x3fb8aa3b, v53
	global_store_short v[78:79], v80, off
	v_exp_f32_e32 v81, v81
	v_lshl_add_u64 v[78:79], v[78:79], 0, v[84:85]
	v_fmac_f32_e32 v29, v28, v81
	v_cvt_pk_bf16_f32 v80, v29, v11
	v_mul_f32_e32 v81, 0x3fb8aa3b, v54
	global_store_short v[78:79], v80, off
	v_exp_f32_e32 v81, v81
	v_lshl_add_u64 v[78:79], v[78:79], 0, v[84:85]
	v_fmac_f32_e32 v30, v29, v81
	v_cvt_pk_bf16_f32 v80, v30, v11
	v_mul_f32_e32 v81, 0x3fb8aa3b, v55
	global_store_short v[78:79], v80, off
	v_exp_f32_e32 v81, v81
	v_lshl_add_u64 v[78:79], v[78:79], 0, v[84:85]
	v_fmac_f32_e32 v31, v30, v81
	v_cvt_pk_bf16_f32 v80, v31, v11
	v_mul_f32_e32 v81, 0x3fb8aa3b, v56
	global_store_short v[78:79], v80, off
	v_exp_f32_e32 v81, v81
	v_lshl_add_u64 v[78:79], v[78:79], 0, v[84:85]
	v_fmac_f32_e32 v32, v31, v81
	v_cvt_pk_bf16_f32 v80, v32, v11
	v_mul_f32_e32 v81, 0x3fb8aa3b, v57
	global_store_short v[78:79], v80, off
	v_exp_f32_e32 v81, v81
	v_lshl_add_u64 v[78:79], v[78:79], 0, v[84:85]
	v_fmac_f32_e32 v33, v32, v81
	v_mov_b32_e32 v12, v33
	s_waitcnt vmcnt(8)
	v_cvt_pk_bf16_f32 v80, v12, v11
	v_mul_f32_e32 v81, 0x3fb8aa3b, v58
	global_store_short v[78:79], v80, off
	v_exp_f32_e32 v81, v81
	v_lshl_add_u64 v[78:79], v[78:79], 0, v[84:85]
	v_fmac_f32_e32 v34, v12, v81
	v_cvt_pk_bf16_f32 v80, v34, v11
	v_mul_f32_e32 v81, 0x3fb8aa3b, v59
	global_store_short v[78:79], v80, off
	v_exp_f32_e32 v81, v81
	v_lshl_add_u64 v[78:79], v[78:79], 0, v[84:85]
	v_fmac_f32_e32 v35, v34, v81
	v_cvt_pk_bf16_f32 v80, v35, v11
	v_mul_f32_e32 v81, 0x3fb8aa3b, v60
	global_store_short v[78:79], v80, off
	v_exp_f32_e32 v81, v81
	v_lshl_add_u64 v[78:79], v[78:79], 0, v[84:85]
	v_fmac_f32_e32 v36, v35, v81
	v_cvt_pk_bf16_f32 v80, v36, v11
	v_mul_f32_e32 v81, 0x3fb8aa3b, v61
	global_store_short v[78:79], v80, off
	v_exp_f32_e32 v81, v81
	v_lshl_add_u64 v[78:79], v[78:79], 0, v[84:85]
	v_fmac_f32_e32 v37, v36, v81
	v_cvt_pk_bf16_f32 v80, v37, v11
	v_mul_f32_e32 v81, 0x3fb8aa3b, v62
	global_store_short v[78:79], v80, off
	v_exp_f32_e32 v81, v81
	v_lshl_add_u64 v[78:79], v[78:79], 0, v[84:85]
	v_fmac_f32_e32 v38, v37, v81
	v_cvt_pk_bf16_f32 v80, v38, v11
	v_mul_f32_e32 v81, 0x3fb8aa3b, v63
	global_store_short v[78:79], v80, off
	v_exp_f32_e32 v81, v81
	v_lshl_add_u64 v[78:79], v[78:79], 0, v[84:85]
	v_fmac_f32_e32 v39, v38, v81
	v_cvt_pk_bf16_f32 v80, v39, v11
	v_mul_f32_e32 v81, 0x3fb8aa3b, v64
	global_store_short v[78:79], v80, off
	v_exp_f32_e32 v81, v81
	v_lshl_add_u64 v[78:79], v[78:79], 0, v[84:85]
	v_fmac_f32_e32 v40, v39, v81
	v_cvt_pk_bf16_f32 v80, v40, v11
	v_mul_f32_e32 v81, 0x3fb8aa3b, v65
	global_store_short v[78:79], v80, off
	v_exp_f32_e32 v81, v81
	v_lshl_add_u64 v[78:79], v[78:79], 0, v[84:85]
	v_fmac_f32_e32 v41, v40, v81
	v_mov_b32_e32 v12, v41
	v_mov_b32_e32 v12, v12
	v_readlane_b32 s4, v243, 17
	s_mov_b32 s2, 0xffff
	s_nop 0
	v_add_u32_e32 v8, s4, v8
	v_cmp_lt_i32_e32 vcc, s2, v8
	s_or_b64 s[10:11], vcc, s[10:11]
	v_add_u16_e32 v9, s4, v9
	s_andn2_b64 exec, exec, s[10:11]
	s_cbranch_execnz .LBB0_729
